# diff phase bias-table fill batched (4 loads, one wait) on top of opt13
# speedup vs baseline: 1.0109x; 1.0022x over previous
; __device__ __forceinline__ void phase_diff_mfma(const PT a, int lyr, unsigned char* ldsb, int tid, int lane, int wave, int bid, int nblk) {
;     ...
;         if (h != hcur) { __syncthreads(); for (int i = tid; i < 2048; i += 512) { tab[i] = biasT[(40 + h) * BT + i] * LOG2E; bk[i] = (unsigned char)t5_bucket(i); } hcur = h; }
.LBB0_348:
	s_and_b32 s2, s70, 7
	s_cmp_eq_u32 s2, s3
	s_cbranch_scc1 .LBB0_355
	s_waitcnt lgkmcnt(0)
	s_barrier
	s_mov_b64 s[0:1], exec
	v_readlane_b32 s4, v253, 42
	v_readlane_b32 s5, v253, 43
	s_and_b64 s[4:5], s[0:1], s[4:5]
	s_mov_b64 exec, s[4:5]
	s_cbranch_execz .LBB0_354
	s_and_b32 s4, s80, 7
	s_mulk_i32 s4, 0x840
	s_add_i32 s4, s4, 0x14a00
	s_mov_b64 s[6:7], 0
	v_mov_b32_e32 v0, v241
	v_mov_b32_e32 v2, v146
	v_add_u32_e32 v4, s4, v2
	v_ashrrev_i32_e32 v5, 31, v4
	v_lshl_add_u64 v[4:5], v[4:5], 2, s[88:89]
	s_mov_b64 s[8:9], 0x1000
	v_lshl_add_u64 v[6:7], v[4:5], 0, s[8:9]
	global_load_dword v8, v[4:5], off
	global_load_dword v9, v[4:5], off offset:2048
	global_load_dword v10, v[6:7], off
	global_load_dword v11, v[6:7], off offset:2048
	v_add_u32_e32 v4, s73, v0
	s_waitcnt vmcnt(0)
	v_mul_f32_e32 v8, 0x3fb8aa3b, v8
	v_mul_f32_e32 v9, 0x3fb8aa3b, v9
	v_mul_f32_e32 v10, 0x3fb8aa3b, v10
	v_mul_f32_e32 v11, 0x3fb8aa3b, v11
	ds_write_b32 v4, v8
	ds_write_b32 v4, v9 offset:2048
	ds_write_b32 v4, v10 offset:4096
	ds_write_b32 v4, v11 offset:6144
	s_branch .LBB0_352

; __device__ __forceinline__ int t5_bucket(int d) {
;     if (d < 16) return d;
;     const float logd = logf((float)d / 16.0f);
;     int far = 16 + (int)(logd / 4.852030263919617f * 16.0f);
;     return far < 31 ? far : 31;
; }
; __device__ __forceinline__ void phase_diff_mfma(const PT a, int lyr, unsigned char* ldsb, int tid, int lane, int wave, int bid, int nblk) {
;     ...
;         if (h != hcur) { __syncthreads(); for (int i = tid; i < 2048; i += 512) { tab[i] = biasT[(40 + h) * BT + i] * LOG2E; bk[i] = (unsigned char)t5_bucket(i); } hcur = h; }
.LBB0_352:
	v_cmp_lt_i32_e32 vcc, 15, v2
	v_mov_b32_e32 v3, v2
	s_and_saveexec_b64 s[8:9], vcc
	s_cbranch_execz .LBB0_351
	v_cvt_f32_u32_e32 v3, v2
	v_mul_f32_e32 v3, 0x3d800000, v3
	v_cmp_gt_f32_e32 vcc, s94, v3
	s_nop 1
	v_cndmask_b32_e64 v4, 0, 32, vcc
	v_ldexp_f32 v3, v3, v4
	v_log_f32_e32 v3, v3
	v_cndmask_b32_e32 v4, 0, v226, vcc
	v_mul_f32_e32 v5, 0x3f317217, v3
	v_fma_f32 v5, v3, s95, -v5
	v_fmac_f32_e32 v5, 0x3377d1cf, v3
	v_fmac_f32_e32 v5, 0x3f317217, v3
	v_cmp_lt_f32_e64 vcc, |v3|, s52
	s_nop 1
	v_cndmask_b32_e32 v3, v3, v5, vcc
	v_sub_f32_e32 v3, v3, v4
	v_div_scale_f32 v4, s[10:11], s54, s54, v3
	v_rcp_f32_e32 v5, v4
	v_div_scale_f32 v6, vcc, v3, s54, v3
	v_fma_f32 v7, -v4, v5, 1.0
	v_fmac_f32_e32 v5, v7, v5
	v_mul_f32_e32 v7, v6, v5
	v_fma_f32 v8, -v4, v7, v6
	v_fmac_f32_e32 v7, v8, v5
	v_fma_f32 v4, -v4, v7, v6
	v_div_fmas_f32 v4, v4, v5, v7
	v_div_fixup_f32 v3, v4, s54, v3
	v_mul_f32_e32 v3, 0x41800000, v3
	v_cvt_i32_f32_e32 v3, v3
	v_min_i32_e32 v3, 15, v3
	v_add_u32_e32 v3, 16, v3
	s_branch .LBB0_351
